# phase 4 reordered (chunk states, arrive, latent q/kv GEMM, wait) + split barrier 5->6, no arrive-time invalidates, placement pads
# baseline (speedup 1.0000x reference)
.LBB0_615:
	s_cmp_lt_i32 s88, 5
	s_cselect_b64 s[12:13], -1, 0
	s_and_b64 s[4:5], s[12:13], s[4:5]
	s_andn2_b64 vcc, exec, s[4:5]
	s_cbranch_vccnz .LBB0_790
	s_load_dword s14, s[0:1], 0x120
	v_lshrrev_b32_e32 v97, 8, v204
	v_mul_u32_u24_e32 v96, 0x12000, v97
	s_waitcnt lgkmcnt(0)
	s_cmpk_lg_i32 s14, 0x100
	s_cselect_b64 s[4:5], -1, 0
	s_waitcnt vmcnt(7)
	v_cndmask_b32_e64 v0, 0, 1, s[4:5]
	s_nop 0
	v_readfirstlane_b32 s6, v0
	s_lshl_b32 s28, s2, s6
.LBB0_757:
	s_cmpk_gt_i32 s28, 0x1ff
	s_cbranch_scc1 .LBB0_790
	s_add_u32 s6, s34, 0xec0c000
	s_addc_u32 s7, s35, 0
	s_add_u32 s8, s34, 0xec8c000
	s_addc_u32 s9, s35, 0
	s_add_u32 s10, s34, 0xed0c000
	s_addc_u32 s11, s35, 0
	s_add_u32 s16, s34, 0xd80c000
	s_load_dwordx16 s[36:51], s[0:1], 0xc0
	s_addc_u32 s17, s35, 0
	s_add_u32 s18, s34, 0xe40c000
	s_addc_u32 s19, s35, 0
	s_waitcnt vmcnt(7)
	v_and_b32_e32 v0, 0x300, v204
	s_add_u32 s20, s34, 0x6a44000
	v_cndmask_b32_e64 v66, v0, v97, s[4:5]
	v_and_b32_e32 v67, 0xff, v204
	v_add_u32_e32 v68, 0x11000, v96
	v_add_u32_e32 v69, 0x11400, v96
	v_add_u32_e32 v70, 0x11800, v96
	v_add_u32_e32 v71, 0x11c00, v96
	s_addc_u32 s21, s35, 0
	s_lshl_b32 s14, s14, 1
	v_add_u32_e32 v72, 0x111fc, v96
	v_add_u32_e32 v73, 0x11200, v96
	v_add_u32_e32 v74, 0x1100c, v96
	v_add_u32_e32 v75, 0x8800, v96
	s_movk_i32 s15, 0x7f
	v_mov_b32_e32 v65, 0
	s_movk_i32 s29, 0x80
	s_waitcnt lgkmcnt(0)
	v_mov_b32_e32 v76, s37
	v_mov_b32_e32 v77, s83
	v_mov_b32_e32 v78, s36
	v_mov_b32_e32 v79, s82
	s_mov_b32 s30, 0x3fb8aa3b
	s_mov_b32 s31, 0xc2ce8ed0
	s_mov_b32 s33, 0x42b17218
	v_mov_b32_e32 v80, 0x7f800000
	s_movk_i32 s36, 0x7d
	s_movk_i32 s37, 0x110
	s_movk_i32 s42, 0x2000
	s_movk_i32 s43, 0x4000
	s_movk_i32 s44, 0x6000

.LBB0_809:
	s_or_b64 exec, exec, s[12:13]
	v_cvt_f32_u32_e32 v4, v2
	s_waitcnt vmcnt(0)
	v_readfirstlane_b32 s10, v3
	v_sub_u32_e32 v3, 0, v2
	v_rcp_iflag_f32_e32 v4, v4
	v_add_u32_e32 v5, s10, v1
	v_mul_f32_e32 v4, 0x4f7ffffe, v4
	v_cvt_u32_f32_e32 v4, v4
	v_mul_lo_u32 v1, v3, v4
	v_mul_hi_u32 v1, v4, v1
	v_add_u32_e32 v1, v4, v1
	v_mul_hi_u32 v1, v5, v1
	v_mul_lo_u32 v3, v1, v2
	v_sub_u32_e32 v3, v5, v3
	v_add_u32_e32 v4, 1, v1
	v_cmp_ge_u32_e32 vcc, v3, v2
	s_nop 1
	v_cndmask_b32_e32 v1, v1, v4, vcc
	v_sub_u32_e32 v4, v3, v2
	v_cndmask_b32_e32 v3, v3, v4, vcc
	v_add_u32_e32 v4, 1, v1
	v_cmp_ge_u32_e32 vcc, v3, v2
	v_add_u32_e32 v3, 1, v5
	s_nop 0
	v_cndmask_b32_e32 v1, v1, v4, vcc
	v_mul_lo_u32 v4, v2, v1
	v_add_u32_e32 v2, v4, v2
	v_cmp_ne_u32_e32 vcc, v3, v2
	s_and_saveexec_b64 s[10:11], vcc
	s_xor_b64 s[10:11], exec, s[10:11]
	s_cbranch_execz .LBB0_823
	s_waitcnt lgkmcnt(0)
	v_mov_b32_e32 v0, 0x24008
	ds_write_b32 v0, v1
	s_waitcnt vmcnt(0)
	s_waitcnt vmcnt(0)

.LBB0_826:
	s_or_b64 exec, exec, s[12:13]
	v_cvt_f32_u32_e32 v3, v0
	s_waitcnt vmcnt(0)
	v_readfirstlane_b32 s10, v2
	s_add_u32 s12, s34, 0xed10500
	s_addc_u32 s13, s35, 0
	v_rcp_iflag_f32_e32 v3, v3
	v_add_u32_e32 v1, s10, v1
	v_add_u32_e32 v4, 1, v1
	s_mov_b64 s[16:17], -1
	v_mul_f32_e32 v2, 0x4f7ffffe, v3
	v_cvt_u32_f32_e32 v2, v2
	v_sub_u32_e32 v3, 0, v0
	v_mul_lo_u32 v3, v3, v2
	v_mul_hi_u32 v3, v2, v3
	v_add_u32_e32 v2, v2, v3
	v_mul_hi_u32 v2, v1, v2
	v_mul_lo_u32 v3, v2, v0
	v_sub_u32_e32 v1, v1, v3
	v_add_u32_e32 v5, 1, v2
	v_cmp_ge_u32_e32 vcc, v1, v0
	v_sub_u32_e32 v3, v1, v0
	s_nop 0
	v_cndmask_b32_e32 v2, v2, v5, vcc
	v_cndmask_b32_e32 v1, v1, v3, vcc
	v_add_u32_e32 v3, 1, v2
	v_cmp_ge_u32_e32 vcc, v1, v0
	s_nop 1
	v_cndmask_b32_e32 v2, v2, v3, vcc
	v_mul_lo_u32 v1, v0, v2
	v_add_u32_e32 v0, v1, v0
	v_mov_b32_e32 v3, 0x24008
	ds_write_b32 v3, v2
	v_cmp_ne_u32_e32 vcc, v4, v0
	v_mov_b64_e32 v[0:1], s[12:13]
	s_and_saveexec_b64 s[10:11], vcc
	s_cbranch_execz .LBB0_838
	s_mov_b64 s[16:17], 0

.LBB0_844:
	s_cmp_gt_i32 s89, 4
	s_cselect_b64 s[4:5], -1, 0
	s_cmp_lt_i32 s88, 5
	s_cselect_b64 s[12:13], -1, 0
	s_and_b64 s[4:5], s[12:13], s[4:5]
	s_andn2_b64 vcc, exec, s[4:5]
	s_cbranch_vccnz .Lq4_done
	s_load_dword s14, s[0:1], 0x120
	v_lshrrev_b32_e32 v97, 8, v204
	v_mul_u32_u24_e32 v96, 0x12000, v97
	s_waitcnt lgkmcnt(0)
	s_cmpk_lg_i32 s14, 0x100
	s_cselect_b64 s[4:5], -1, 0
	s_waitcnt vmcnt(7)
	v_cndmask_b32_e64 v0, 0, 1, s[4:5]
	s_nop 0
	v_readfirstlane_b32 s6, v0
	s_lshl_b32 s28, s2, s6
	s_cmpk_gt_i32 s28, 0x39f
	s_cbranch_scc1 .Lq4_done
	v_and_b32_e32 v0, 0x300, v204
	v_cndmask_b32_e64 v36, v0, v97, s[4:5]
	v_add_u32_e32 v0, s28, v36
	s_waitcnt vmcnt(6)
	v_min_i32_e32 v5, 0x39f, v0
	s_movk_i32 s6, 0x17f
	v_and_b32_e32 v37, 0xff, v204
	v_cmp_lt_i32_e32 vcc, s6, v0
	v_and_b32_e32 v6, 7, v5
	s_and_saveexec_b64 s[6:7], vcc
	s_xor_b64 s[6:7], exec, s[6:7]
	s_cbranch_execz .LBB0_619
	v_add_u32_e32 v0, 0xfffffe80, v5
	v_lshrrev_b32_e32 v0, 3, v0
	s_movk_i32 s8, 0x44
	v_mad_u32_u24 v0, v6, s8, v0
	v_lshrrev_b32_e32 v1, 3, v0
	v_and_b32_e32 v1, 0x7fffff8, v1
	v_sub_u32_e32 v2, 0x44, v1
	v_min_u32_e32 v2, 8, v2
	v_cvt_f32_ubyte0_e32 v3, v2
	v_rcp_iflag_f32_e32 v4, v3
	v_and_b32_e32 v0, 63, v0
	v_cvt_f32_ubyte0_e32 v5, v0
	v_mov_b32_e32 v111, 0
	v_mul_f32_e32 v4, v5, v4
	v_trunc_f32_e32 v4, v4
	v_cvt_u32_f32_e32 v6, v4
	v_fma_f32 v4, -v4, v3, v5
	v_cmp_ge_f32_e64 vcc, |v4|, v3
	s_nop 1
	v_addc_co_u32_e32 v3, vcc, 0, v6, vcc
	v_mul_lo_u16_e32 v2, v3, v2
	v_sub_u16_e32 v0, v0, v2
	v_and_b32_e32 v0, 0xff, v0
	v_and_b32_e32 v4, 0xff, v3
	v_add_lshl_u32 v110, v1, v0, 7

.Lq4_done:
	s_cmp_gt_i32 s88, 4
	s_cbranch_scc1 .Lsb4_skip
	s_cmp_lt_i32 s89, 6
	s_cbranch_scc1 .Lsb4_skip
	s_waitcnt vmcnt(0) lgkmcnt(0)
	s_and_saveexec_b64 s[16:17], s[92:93]
	s_cbranch_execz .Lsb4_done
	v_mov_b32_e32 v0, 0x24008
	ds_read_b32 v1, v0
	buffer_inv sc1
	s_add_u32 s18, s34, 0xed10500
	s_addc_u32 s19, s35, 0
	v_mov_b32_e32 v0, 0
	s_mov_b32 s20, 0
	s_waitcnt lgkmcnt(0)

.Lsb4_skip:
	s_load_dwordx16 s[36:51], s[0:1], 0xc0
	s_cmp_gt_i32 s89, 5
	s_cselect_b64 s[4:5], -1, 0
	s_waitcnt lgkmcnt(0)
	s_cmp_lt_i32 s88, 6
	s_cselect_b64 s[6:7], -1, 0
	s_and_b64 s[4:5], s[6:7], s[4:5]
	s_andn2_b64 vcc, exec, s[4:5]
	s_cbranch_vccnz .LBB0_853
	s_waitcnt vmcnt(5)
	v_lshl_add_u32 v8, s2, 9, v204
	s_mov_b32 s4, 0x90000
	v_cmp_gt_i32_e32 vcc, s4, v8
	s_and_saveexec_b64 s[4:5], vcc
	s_cbranch_execz .LBB0_852
	s_load_dword s15, s[0:1], 0x120
	v_lshlrev_b32_e32 v0, 2, v204
	v_mov_b32_e32 v1, 0
	s_mov_b64 s[8:9], 0
	v_lshl_add_u32 v9, s2, 11, v0
	s_waitcnt lgkmcnt(0)
	s_lshl_b32 s14, s15, 9
	s_add_u32 s10, s34, 0xed0c000
	s_addc_u32 s11, s35, 0
	s_add_u32 s12, s34, 0x6a44000
	s_addc_u32 s13, s35, 0
	s_add_u32 s16, s34, 0x8a44000
	s_addc_u32 s17, s35, 0
	s_lshl_b32 s15, s15, 11
	s_mov_b32 s20, 0x38e38e39
	s_movk_i32 s21, 0xffdc
	s_movk_i32 s22, 0xffdd
	s_movk_i32 s23, 0xff20
	s_mov_b32 s24, 0x8ffff
	s_waitcnt vmcnt(4)
	v_mov_b32_e32 v14, v1
	v_mov_b32_e32 v15, v1
	v_mov_b32_e32 v10, 0x2880000
	v_mov_b32_e32 v11, 0x2480000
	s_branch .LBB0_848
